# cache-policy hint: nt on the HM head-norm stores streamed inside attention (less L2 pollution next to the shared K/V blocks)
# speedup vs baseline: 1.0049x; 1.0049x over previous
; __device__ __forceinline__ void st_wt16(void* p, u32x4 v) { asm volatile("global_store_dwordx4 %0, %1, off sc1\n\ts_nop 1" : : "v"(p), "v"(v) : "memory"); }
; __device__ __forceinline__ void p5_fixup(const Params& p) {
;     ...
;     for (int v0 = gtid; v0 < T_TOK * 128; v0 += 4 * gsz) {
;         u32x4 hv[4]; float4 s0[4], s1[4];
; #pragma unroll
;         for (int u = 0; u < 4; ++u) { const int v = v0 + u * gsz; if (v < T_TOK * 128) { const int row = v >> 7, head = (v >> 5) & 3;
;             hv[u] = __builtin_nontemporal_load((const u32x4*)(HM + (size_t)v * 8)); s0[u] = *(const float4*)(SSQ + ((size_t)row * 4 + head) * 8); s1[u] = *(const float4*)(SSQ + ((size_t)row * 4 + head) * 8 + 4); } }
; #pragma unroll
;         for (int u = 0; u < 4; ++u) { const int v = v0 + u * gsz; if (v < T_TOK * 128) {
;             const float ss = (s0[u].x + s0[u].y) + (s0[u].z + s0[u].w) + (s1[u].x + s1[u].y) + (s1[u].z + s1[u].w);
;             const float rstd = rsqrtf(ss * (1.0f / 256.0f) + EPS);
;             float f[8]; unpack8(hv[u], f);
; #pragma unroll
;             for (int e = 0; e < 8; ++e) f[e] *= rstd;
;             st_wt16(HM + (size_t)v * 8, pack8(f)); } }
.Lattn_pf_done:
	s_cmp_gt_u32 s98, 3
	s_cbranch_scc1 .Lhm_noconsume
	v_add_f32_dpp v246, v246, v246 quad_perm:[1,0,3,2] row_mask:0xf bank_mask:0xf
	v_add_f32_dpp v247, v247, v247 quad_perm:[1,0,3,2] row_mask:0xf bank_mask:0xf
	v_add_f32_dpp v248, v248, v248 quad_perm:[1,0,3,2] row_mask:0xf bank_mask:0xf
	v_add_f32_dpp v249, v249, v249 quad_perm:[1,0,3,2] row_mask:0xf bank_mask:0xf
	v_add_f32_dpp v246, v246, v246 quad_perm:[2,3,0,1] row_mask:0xf bank_mask:0xf
	v_add_f32_dpp v247, v247, v247 quad_perm:[2,3,0,1] row_mask:0xf bank_mask:0xf
	v_add_f32_dpp v248, v248, v248 quad_perm:[2,3,0,1] row_mask:0xf bank_mask:0xf
	v_add_f32_dpp v249, v249, v249 quad_perm:[2,3,0,1] row_mask:0xf bank_mask:0xf
	v_add_f32_dpp v246, v246, v246 row_half_mirror row_mask:0xf bank_mask:0xf
	v_add_f32_dpp v247, v247, v247 row_half_mirror row_mask:0xf bank_mask:0xf
	v_add_f32_dpp v248, v248, v248 row_half_mirror row_mask:0xf bank_mask:0xf
	v_add_f32_dpp v249, v249, v249 row_half_mirror row_mask:0xf bank_mask:0xf
	v_mov_b32_e32 v252, 0x358637bd
	v_mov_b32_e32 v255, s98
	v_fmamk_f32 v246, v246, 0x3b800000, v252
	v_fmamk_f32 v247, v247, 0x3b800000, v252
	v_fmamk_f32 v248, v248, 0x3b800000, v252
	v_fmamk_f32 v249, v249, 0x3b800000, v252
	v_rsq_f32_e32 v246, v246
	v_rsq_f32_e32 v247, v247
	v_rsq_f32_e32 v248, v248
	v_rsq_f32_e32 v249, v249
	v_lshl_add_u32 v255, v255, 23, v250
	v_lshlrev_b32_e32 v252, 16, v230
	v_and_b32_e32 v253, 0xffff0000, v230
	v_mul_f32_e32 v252, v246, v252
	v_mul_f32_e32 v253, v246, v253
	v_cvt_pk_bf16_f32 v230, v252, v253
	v_lshlrev_b32_e32 v252, 16, v231
	v_and_b32_e32 v253, 0xffff0000, v231
	v_mul_f32_e32 v252, v246, v252
	v_mul_f32_e32 v253, v246, v253
	v_cvt_pk_bf16_f32 v231, v252, v253
	v_lshlrev_b32_e32 v252, 16, v232
	v_and_b32_e32 v253, 0xffff0000, v232
	v_mul_f32_e32 v252, v246, v252
	v_mul_f32_e32 v253, v246, v253
	v_cvt_pk_bf16_f32 v232, v252, v253
	v_lshlrev_b32_e32 v252, 16, v233
	v_and_b32_e32 v253, 0xffff0000, v233
	v_mul_f32_e32 v252, v246, v252
	v_mul_f32_e32 v253, v246, v253
	v_cvt_pk_bf16_f32 v233, v252, v253
	global_store_dwordx4 v255, v[230:233], s[100:101] nt
	v_add_u32_e32 v255, 0x2000, v255
	v_lshlrev_b32_e32 v252, 16, v234
	v_and_b32_e32 v253, 0xffff0000, v234
	v_mul_f32_e32 v252, v247, v252
	v_mul_f32_e32 v253, v247, v253
	v_cvt_pk_bf16_f32 v234, v252, v253
	v_lshlrev_b32_e32 v252, 16, v235
	v_and_b32_e32 v253, 0xffff0000, v235
	v_mul_f32_e32 v252, v247, v252
	v_mul_f32_e32 v253, v247, v253
	v_cvt_pk_bf16_f32 v235, v252, v253
	v_lshlrev_b32_e32 v252, 16, v236
	v_and_b32_e32 v253, 0xffff0000, v236
	v_mul_f32_e32 v252, v247, v252
	v_mul_f32_e32 v253, v247, v253
	v_cvt_pk_bf16_f32 v236, v252, v253
	v_lshlrev_b32_e32 v252, 16, v237
	v_and_b32_e32 v253, 0xffff0000, v237
	v_mul_f32_e32 v252, v247, v252
	v_mul_f32_e32 v253, v247, v253
	v_cvt_pk_bf16_f32 v237, v252, v253
	global_store_dwordx4 v255, v[234:237], s[100:101] nt
	v_add_u32_e32 v255, 0x2000, v255
	v_lshlrev_b32_e32 v252, 16, v238
	v_and_b32_e32 v253, 0xffff0000, v238
	v_mul_f32_e32 v252, v248, v252
	v_mul_f32_e32 v253, v248, v253
	v_cvt_pk_bf16_f32 v238, v252, v253
	v_lshlrev_b32_e32 v252, 16, v239
	v_and_b32_e32 v253, 0xffff0000, v239
	v_mul_f32_e32 v252, v248, v252
	v_mul_f32_e32 v253, v248, v253
	v_cvt_pk_bf16_f32 v239, v252, v253
	v_lshlrev_b32_e32 v252, 16, v240
	v_and_b32_e32 v253, 0xffff0000, v240
	v_mul_f32_e32 v252, v248, v252
	v_mul_f32_e32 v253, v248, v253
	v_cvt_pk_bf16_f32 v240, v252, v253
	v_lshlrev_b32_e32 v252, 16, v241
	v_and_b32_e32 v253, 0xffff0000, v241
	v_mul_f32_e32 v252, v248, v252
	v_mul_f32_e32 v253, v248, v253
	v_cvt_pk_bf16_f32 v241, v252, v253
	global_store_dwordx4 v255, v[238:241], s[100:101] nt
	v_add_u32_e32 v255, 0x2000, v255
	v_lshlrev_b32_e32 v252, 16, v242
	v_and_b32_e32 v253, 0xffff0000, v242
	v_mul_f32_e32 v252, v249, v252
	v_mul_f32_e32 v253, v249, v253
	v_cvt_pk_bf16_f32 v242, v252, v253
	v_lshlrev_b32_e32 v252, 16, v243
	v_and_b32_e32 v253, 0xffff0000, v243
	v_mul_f32_e32 v252, v249, v252
	v_mul_f32_e32 v253, v249, v253
	v_cvt_pk_bf16_f32 v243, v252, v253
	v_lshlrev_b32_e32 v252, 16, v244
	v_and_b32_e32 v253, 0xffff0000, v244
	v_mul_f32_e32 v252, v249, v252
	v_mul_f32_e32 v253, v249, v253
	v_cvt_pk_bf16_f32 v244, v252, v253
	v_lshlrev_b32_e32 v252, 16, v245
	v_and_b32_e32 v253, 0xffff0000, v245
	v_mul_f32_e32 v252, v249, v252
	v_mul_f32_e32 v253, v249, v253
	v_cvt_pk_bf16_f32 v245, v252, v253
	global_store_dwordx4 v255, v[242:245], s[100:101] nt
	s_nop 1
